# final norm row loop: g_final gamma loads (loop-invariant) loaded once before the loop; no store-ack waits in the row tail
# speedup vs baseline: 1.0071x; 1.0071x over previous
; DI unsigned pack2(float a, float b) { f2_t v = {a, b}; return __builtin_bit_cast(unsigned, __builtin_convertvector(v, bf2_t)); }
; DI int otid() { int t = threadIdx.x; asm volatile("" : "+v"(t)); return t; }
; template <int MODE>
; DI void phase_norm(const float* xin, const float* g, const float* modl, int sh_off, int sc_off, u16* hout, float* fout) {
;   const int tid = otid(); const int lane = tid & 63, w = tid >> 6;
;   for (int row = blockIdx.x * NWAVE + w; row < NTOK; row += gridDim.x * NWAVE) {
;     const int b = row >> 14;
;     const float4* xr = (const float4*)(xin + (size_t)row * 1024);
;     float4 v[4];
; #pragma unroll
;     for (int i = 0; i < 4; ++i) v[i] = xr[lane + i * 64];
;     float ss = 0.f;
; #pragma unroll
;     for (int i = 0; i < 4; ++i) ss += v[i].x * v[i].x + v[i].y * v[i].y + v[i].z * v[i].z + v[i].w * v[i].w;
;     ss = wave_sum(ss);
;     const float inv = rsqrtf(ss * (1.f / 1024.f) + 1e-6f);
; #pragma unroll
;     for (int i = 0; i < 4; ++i) {
;       const int col = (lane + i * 64) * 4;
;       const float4 g4 = *(const float4*)(g + col);
;       if (MODE == 0) {
;         const float4 sc4 = *(const float4*)(modl + b * 6144 + sc_off + col);
;         const float4 sh4 = *(const float4*)(modl + b * 6144 + sh_off + col);
;         float y0 = v[i].x * inv * g4.x * (1.f + sc4.x) + sh4.x;
;         float y1 = v[i].y * inv * g4.y * (1.f + sc4.y) + sh4.y;
;         float y2 = v[i].z * inv * g4.z * (1.f + sc4.z) + sh4.z;
;         float y3 = v[i].w * inv * g4.w * (1.f + sc4.w) + sh4.w;
;         *(uint2*)(hout + (size_t)row * 1024 + col) = make_uint2(pack2(y0, y1), pack2(y2, y3));
;       } else {
;         float4 y; y.x = v[i].x * inv * g4.x; y.y = v[i].y * inv * g4.y; y.z = v[i].z * inv * g4.z; y.w = v[i].w * inv * g4.w;
;         *(float4*)(fout + (size_t)row * 1024 + col) = y;
;       }
.LBB0_841:
	v_readlane_b32 s0, v254, 4
	v_ashrrev_i32_e32 v0, 6, v224
	s_nop 0
	v_add_u32_e32 v0, s0, v0
	s_mov_b32 s0, 0x8000
	v_cmp_gt_i32_e32 vcc, s0, v0
	s_and_saveexec_b64 s[0:1], vcc
	s_cbranch_execz .LBB0_844
	s_load_dwordx4 s[4:7], s[82:83], 0x78
	v_and_b32_e32 v6, 63, v224
	v_mov_b32_e32 v3, 0
	v_lshlrev_b32_e32 v8, 2, v6
	v_lshlrev_b32_e32 v2, 4, v6
	s_waitcnt lgkmcnt(0)
	v_lshl_add_u64 v[4:5], s[4:5], 0, v[2:3]
	s_mov_b64 s[0:1], 0
	v_lshlrev_b32_e32 v2, 4, v6
	v_lshlrev_b32_e32 v6, 2, v8
	v_mov_b32_e32 v7, v3
	v_mov_b32_e32 v8, 0x358637bd
	s_mov_b32 s2, 0x800000
	s_movk_i32 s4, 0x7fff
	global_load_dwordx4 v[48:51], v[4:5], off
	global_load_dwordx4 v[52:55], v[4:5], off offset:1024
	global_load_dwordx4 v[56:59], v[4:5], off offset:2048
	global_load_dwordx4 v[60:63], v[4:5], off offset:3072
	s_waitcnt vmcnt(0)
.LBB0_843:
	v_ashrrev_i32_e32 v1, 31, v0
	v_lshlrev_b64 v[10:11], 12, v[0:1]
	v_lshl_add_u64 v[30:31], s[6:7], 0, v[10:11]
	v_lshl_add_u64 v[32:33], v[30:31], 0, v[2:3]
	global_load_dwordx4 v[10:13], v[32:33], off
	global_load_dwordx4 v[14:17], v[32:33], off offset:1024
	global_load_dwordx4 v[18:21], v[32:33], off offset:2048
	global_load_dwordx4 v[22:25], v[32:33], off offset:3072
	v_lshl_add_u64 v[30:31], v[30:31], 0, v[6:7]
	v_add_u32_e32 v0, s3, v0
	s_waitcnt vmcnt(3)
	v_mov_b32_e32 v34, v11
	s_waitcnt vmcnt(2)
	v_mov_b32_e32 v35, v15
	v_mov_b32_e32 v32, v10
	v_mov_b32_e32 v33, v14
	s_waitcnt vmcnt(1)
	v_mov_b32_e32 v42, v19
	s_waitcnt vmcnt(0)
	v_mov_b32_e32 v43, v23
	v_pk_mul_f32 v[34:35], v[34:35], v[34:35]
	v_mov_b32_e32 v36, v12
	v_mov_b32_e32 v37, v16
	v_mov_b32_e32 v40, v18
	v_mov_b32_e32 v41, v22
	v_pk_mul_f32 v[42:43], v[42:43], v[42:43]
	v_pk_fma_f32 v[32:33], v[32:33], v[32:33], v[34:35]
	v_mov_b32_e32 v38, v13
	v_mov_b32_e32 v39, v17
	v_mov_b32_e32 v44, v20
	v_mov_b32_e32 v45, v24
	v_pk_fma_f32 v[34:35], v[40:41], v[40:41], v[42:43]
	v_pk_fma_f32 v[32:33], v[36:37], v[36:37], v[32:33]
	v_mov_b32_e32 v46, v21
	v_mov_b32_e32 v47, v25
	v_pk_fma_f32 v[34:35], v[44:45], v[44:45], v[34:35]
	v_pk_fma_f32 v[32:33], v[38:39], v[38:39], v[32:33]
	v_pk_fma_f32 v[34:35], v[46:47], v[46:47], v[34:35]
	v_add_f32_e32 v1, v32, v33
	v_add_f32_e32 v1, v1, v34
	v_add_f32_e32 v1, v1, v35
	ds_bpermute_b32 v9, v242, v1
	s_waitcnt lgkmcnt(0)
	v_add_f32_e32 v1, v1, v9
	ds_bpermute_b32 v9, v243, v1
	s_waitcnt lgkmcnt(0)
	v_add_f32_e32 v1, v1, v9
	ds_bpermute_b32 v9, v244, v1
	s_waitcnt lgkmcnt(0)
	v_add_f32_e32 v1, v1, v9
	ds_bpermute_b32 v9, v245, v1
	s_waitcnt lgkmcnt(0)
	v_add_f32_e32 v1, v1, v9
	ds_bpermute_b32 v9, v246, v1
	s_waitcnt lgkmcnt(0)
	v_add_f32_e32 v1, v1, v9
	ds_bpermute_b32 v9, v247, v1
	s_waitcnt lgkmcnt(0)
	v_add_f32_e32 v1, v1, v9
	v_fmamk_f32 v1, v1, 0x3a800000, v8
	v_mul_f32_e32 v9, 0x4b800000, v1
	v_cmp_gt_f32_e32 vcc, s2, v1
	s_nop 1
	v_cndmask_b32_e32 v1, v1, v9, vcc
	v_rsq_f32_e32 v1, v1
	s_nop 0
	v_mul_f32_e32 v9, 0x45800000, v1
	v_cndmask_b32_e32 v32, v1, v9, vcc
	v_pk_mul_f32 v[10:11], v[10:11], v[32:33] op_sel_hi:[1,0]
	v_pk_mul_f32 v[12:13], v[12:13], v[32:33] op_sel_hi:[1,0]
	v_pk_mul_f32 v[10:11], v[48:49], v[10:11]
	v_pk_mul_f32 v[12:13], v[50:51], v[12:13]
	global_store_dwordx4 v[30:31], v[10:13], off
	s_nop 1
	v_pk_mul_f32 v[14:15], v[14:15], v[32:33] op_sel_hi:[1,0]
	v_pk_mul_f32 v[16:17], v[16:17], v[32:33] op_sel_hi:[1,0]
	v_cmp_lt_i32_e32 vcc, s4, v0
	s_or_b64 s[0:1], vcc, s[0:1]
	v_pk_mul_f32 v[10:11], v[52:53], v[14:15]
	v_pk_mul_f32 v[12:13], v[54:55], v[16:17]
	global_store_dwordx4 v[30:31], v[10:13], off offset:1024
	s_nop 1
	v_pk_mul_f32 v[14:15], v[18:19], v[32:33] op_sel_hi:[1,0]
	v_pk_mul_f32 v[16:17], v[20:21], v[32:33] op_sel_hi:[1,0]
	v_pk_mul_f32 v[10:11], v[14:15], v[56:57]
	v_pk_mul_f32 v[12:13], v[16:17], v[58:59]
	global_store_dwordx4 v[30:31], v[10:13], off offset:2048
	s_nop 1
	v_pk_mul_f32 v[14:15], v[22:23], v[32:33] op_sel_hi:[1,0]
	v_pk_mul_f32 v[16:17], v[24:25], v[32:33] op_sel_hi:[1,0]
	v_pk_mul_f32 v[10:11], v[14:15], v[60:61]
	v_pk_mul_f32 v[12:13], v[16:17], v[62:63]
	global_store_dwordx4 v[30:31], v[10:13], off offset:3072
	s_nop 1
	s_andn2_b64 exec, exec, s[0:1]
	s_cbranch_execnz .LBB0_843
